# weight transposes of all layers but the first in-projection moved out of phase 0 into the idle last rounds of the first even / first odd in-projection GEMMs (hand-written 64x32 f32->bf16 transposer)
# speedup vs baseline: 1.0165x; 1.0035x over previous
; #define LAS __attribute__((address_space(3)))
; __device__ __forceinline__ unsigned pk2(float lo, float hi) { return f2bf(lo) | (f2bf(hi) << 16); }
; __device__ __forceinline__ void p0_transpose_item(const float* W, int K, int N, bf16_t* WT, LAS float* scr, int item, int lane) {
;     const int nblk = N / 32, kb = item / nblk, nb = item % nblk, k0 = 64 * kb, n0 = 32 * nb;
;     float tv[32];
; #pragma unroll
;     for (int i = 0; i < 32; ++i) tv[i] = W[(size_t)(k0 + 2 * i + (lane >> 5)) * N + n0 + (lane & 31)];
; #pragma unroll
;     for (int i = 0; i < 32; ++i) scr[(2 * i + (lane >> 5)) * 33 + (lane & 31)] = tv[i];
;     asm volatile("s_waitcnt lgkmcnt(0)" ::: "memory");
;     const int c = lane & 7;
; #pragma unroll
;     for (int j = 0; j < 4; ++j) { const int n = (lane >> 3) + 8 * j; const LAS float* s = scr + (8 * c) * 33 + n;
;         u32x4 o; o.x = pk2(s[0 * 33], s[1 * 33]); o.y = pk2(s[2 * 33], s[3 * 33]); o.z = pk2(s[4 * 33], s[5 * 33]); o.w = pk2(s[6 * 33], s[7 * 33]);
;         *(u32x4*)(WT + (size_t)(n0 + n) * K + k0 + 8 * c) = o; }
;     asm volatile("s_waitcnt lgkmcnt(0)" ::: "memory");
; }
; __device__ __forceinline__ void phase0(const Params& p, LAS unsigned char* lds, int gw, int NGW, int wave, int lane) {
;     LAS float* scr = (LAS float*)(lds + wave * 16384);
;     unsigned char* ws = p.ws;
;     constexpr int I_EI = (1024 / 64) * (EIN / 32), I_EO = (1024 / 64) * (1024 / 32), I_OI = (1024 / 64) * (OIN / 32), I_OO = (512 / 64) * (1024 / 32);
;     constexpr int NIT = 2 * (I_EI + I_EO + I_OI + I_OO);
;     for (int it = gw; it < NIT; it += NGW) {
;         int r = it;
;         if (r < 2 * I_EI) { const int j = r / I_EI; p0_transpose_item(p.in[8] + (size_t)j * 1024 * EIN, 1024, EIN, (bf16_t*)(ws + WS_WEI) + (size_t)j * EINP * 1024, scr, r % I_EI, lane); continue; } r -= 2 * I_EI;
.LBB0_8:
	s_lshl_b32 s60, s90, 3
	s_lshl_b32 s4, s71, 3
	s_add_u32 s0, s88, 0x2900000
	v_writelane_b32 v251, s0, 2
	s_addc_u32 s0, s89, 0
	v_writelane_b32 v251, s0, 3
	s_add_u32 s0, s88, 0x1500000
	v_writelane_b32 v251, s0, 4
	s_addc_u32 s0, s89, 0
	v_writelane_b32 v251, s0, 5
	s_add_u32 s0, s88, 0x1100000
	v_writelane_b32 v251, s0, 6
	s_addc_u32 s0, s89, 0
	v_writelane_b32 v251, s0, 7
	s_mov_b32 s0, -1
	v_readlane_b32 s1, v251, 0
	s_mov_b32 s5, 0
	v_mbcnt_lo_u32_b32 v2, s0, 0
	v_mbcnt_hi_u32_b32 v3, s0, v2
	s_add_i32 s0, s1, s4
	v_writelane_b32 v251, s4, 8
	s_cmpk_lt_i32 s0, 0x840
	v_lshlrev_b32_e32 v2, 3, v3
	s_cbranch_scc0 .LBB0_23
	s_lshl_b32 s1, s1, 14
	v_lshrrev_b32_e32 v8, 5, v3
	v_and_b32_e32 v4, 31, v3
	s_add_i32 s1, s1, 0
	v_lshlrev_b32_e32 v6, 2, v4
	v_mul_u32_u24_e32 v7, 0x84, v8
	v_add3_u32 v9, s1, v6, v7
	v_lshrrev_b32_e32 v10, 3, v3
	v_and_b32_e32 v6, 56, v2
	v_mul_u32_u24_e32 v7, 0x84, v6
	v_lshlrev_b32_e32 v11, 2, v10
	v_add3_u32 v11, s1, v7, v11
	s_lshl_b32 s1, s0, 1
	v_mov_b32_e32 v5, 0
	v_add_u32_e32 v12, 8, v10
	v_or_b32_e32 v13, 16, v10
	v_add_u32_e32 v14, 24, v10
	s_addk_i32 s1, 0xaf00
	s_lshl_b32 s16, s60, 1
	s_lshl_b32 s17, s0, 5
	s_lshl_b32 s18, s60, 5
	s_movk_i32 s20, 0x2000
	s_movk_i32 s21, 0x6000
	s_mov_b32 s22, 0xa000
	s_mov_b32 s23, 0xe000
	s_mov_b32 s24, 0x12000
	s_mov_b32 s25, 0x16000
	s_mov_b32 s26, 0x1a000
	s_mov_b32 s27, 0x1e000
	s_mov_b32 s28, 0x22000
	s_mov_b32 s29, 0x26000
	s_mov_b32 s30, 0x2a000
	s_mov_b32 s31, 0x2e000
	s_mov_b32 s33, 0x32000
	s_mov_b32 s34, 0x36000
	s_mov_b32 s35, 0x3a000
	s_mov_b32 s36, 0x3e000
	s_movk_i32 s37, 0x7fff
	s_mov_b32 s38, 0xffff0000
	s_movk_i32 s39, 0x5000
	s_movk_i32 s40, 0x4200
	v_lshlrev_b32_e32 v4, 2, v4
	v_add_u32_e32 v15, 0x400, v9
	v_add_u32_e32 v16, 0x800, v9
	v_add_u32_e32 v17, 0xc00, v9
	v_add_u32_e32 v18, 0x1000, v9
	v_add_u32_e32 v19, 0x1400, v9
	v_add_u32_e32 v20, 0x1800, v9
	v_add_u32_e32 v21, 0x1c00, v9
	v_lshlrev_b32_e32 v6, 1, v6
	s_mov_b32 s41, s0
	s_branch .LBB0_11
.LBB0_10:
	s_add_i32 s41, s41, s60
	s_add_i32 s1, s1, s16
	s_add_i32 s17, s17, s18
	s_cmpk_gt_i32 s41, 0x83f
	s_cbranch_scc1 .LBB0_23

; #define LAS __attribute__((address_space(3)))
; __device__ __forceinline__ unsigned pk2(float lo, float hi) { return f2bf(lo) | (f2bf(hi) << 16); }
; __device__ __forceinline__ void p0_transpose_item(const float* W, int K, int N, bf16_t* WT, LAS float* scr, int item, int lane) {
;     const int nblk = N / 32, kb = item / nblk, nb = item % nblk, k0 = 64 * kb, n0 = 32 * nb;
;     float tv[32];
; #pragma unroll
;     for (int i = 0; i < 32; ++i) tv[i] = W[(size_t)(k0 + 2 * i + (lane >> 5)) * N + n0 + (lane & 31)];
; #pragma unroll
;     for (int i = 0; i < 32; ++i) scr[(2 * i + (lane >> 5)) * 33 + (lane & 31)] = tv[i];
;     asm volatile("s_waitcnt lgkmcnt(0)" ::: "memory");
;     const int c = lane & 7;
; #pragma unroll
;     for (int j = 0; j < 4; ++j) { const int n = (lane >> 3) + 8 * j; const LAS float* s = scr + (8 * c) * 33 + n;
;         u32x4 o; o.x = pk2(s[0 * 33], s[1 * 33]); o.y = pk2(s[2 * 33], s[3 * 33]); o.z = pk2(s[4 * 33], s[5 * 33]); o.w = pk2(s[6 * 33], s[7 * 33]);
;         *(u32x4*)(WT + (size_t)(n0 + n) * K + k0 + 8 * c) = o; }
;     asm volatile("s_waitcnt lgkmcnt(0)" ::: "memory");
; }
; __device__ __forceinline__ void phase0(const Params& p, LAS unsigned char* lds, int gw, int NGW, int wave, int lane) {
;     ...
;     for (int it = gw; it < NIT; it += NGW) {
;         int r = it;
;         if (r < 2 * I_EI) { const int j = r / I_EI; p0_transpose_item(p.in[8] + (size_t)j * 1024 * EIN, 1024, EIN, (bf16_t*)(ws + WS_WEI) + (size_t)j * EINP * 1024, scr, r % I_EI, lane); continue; } r -= 2 * I_EI;
;         if (r < 2 * I_EO) { const int j = r / I_EO; p0_transpose_item(p.in[9] + (size_t)j * 1024 * 1024, 1024, 1024, (bf16_t*)(ws + WS_WEO) + (size_t)j * 1024 * 1024, scr, r % I_EO, lane); continue; } r -= 2 * I_EO;
;         if (r < 2 * I_OI) { const int j = r / I_OI; p0_transpose_item(p.in[21] + (size_t)j * 1024 * OIN, 1024, OIN, (bf16_t*)(ws + WS_WOI) + (size_t)j * OIN * 1024, scr, r % I_OI, lane); continue; } r -= 2 * I_OI;
;         { const int j = r / I_OO; p0_transpose_item(p.in[22] + (size_t)j * 512 * 1024, 512, 1024, (bf16_t*)(ws + WS_WOO) + (size_t)j * 1024 * 512, scr, r % I_OO, lane); }
;     }
.Lwt_o_begin:
	v_readlane_b32 s100, v255, 18
	v_mbcnt_lo_u32_b32 v2, -1, 0
	v_mbcnt_hi_u32_b32 v2, -1, v2
	s_cmp_lg_u32 s100, 0
	s_cbranch_scc1 .Lkvc_o_done
	s_cmp_eq_u32 s90, 0x100
	s_cselect_b32 s100, 20, 0
	s_sub_u32 s101, s90, s100
	s_lshl_b32 s101, s101, 3
	v_mov_b32_e32 v1, s101
	s_sub_u32 s100, s71, s100
	s_lshl_b32 s100, s100, 3
	v_readlane_b32 s101, v251, 0
	s_nop 1
	s_add_u32 s100, s100, s101
	v_mov_b32_e32 v0, s100
	s_nop 1
.Lwt_o_loop:
	v_readfirstlane_b32 s100, v0
	s_nop 1
	s_cmp_ge_u32 s100, 2816
	s_cbranch_scc1 .Lkvc_o_done
	s_cmp_lt_u32 s100, 2560
	s_cbranch_scc1 .Lwt_o_c0
	s_branch .Lwt_o_c1
.Lwt_o_c0:
	v_mov_b32_e32 v20, v0
	v_mov_b32_e32 v4, 0x199999a
	v_mul_hi_u32 v6, v20, v4
	v_mul_u32_u24_e32 v7, 160, v6
	v_sub_u32_e32 v7, v20, v7
	v_lshlrev_b32_e32 v6, 6, v6
	v_lshlrev_b32_e32 v7, 5, v7
	v_mov_b32_e32 v8, 0x5000
	v_mov_b32_e32 v9, 0x800
	v_readlane_b32 s100, v251, 51
	v_readlane_b32 s101, v251, 52
	s_nop 1
	s_add_u32 s100, s100, 0x1400000
	s_addc_u32 s101, s101, 0
	v_mov_b32_e32 v10, s100
	v_mov_b32_e32 v11, s101
	s_add_u32 s100, s88, 0x1f00000
	s_addc_u32 s101, s89, 0
	v_mov_b32_e32 v12, s100
	v_mov_b32_e32 v13, s101
	s_branch .Lwt_o_body
.Lwt_o_c1:
	v_subrev_u32_e32 v20, 2560, v0
	v_mov_b32_e32 v4, 0x8000000
	v_mul_hi_u32 v6, v20, v4
	v_mul_u32_u24_e32 v7, 32, v6
	v_sub_u32_e32 v7, v20, v7
	v_lshlrev_b32_e32 v6, 6, v6
	v_lshlrev_b32_e32 v7, 5, v7
	v_mov_b32_e32 v8, 0x1000
	v_mov_b32_e32 v9, 0x400
	v_readlane_b32 s100, v251, 53
	v_readlane_b32 s101, v251, 54
	s_nop 1
	s_add_u32 s100, s100, 0x200000
	s_addc_u32 s101, s101, 0
	v_mov_b32_e32 v10, s100
	v_mov_b32_e32 v11, s101
	s_add_u32 s100, s88, 0x2a00000
	s_addc_u32 s101, s89, 0
	v_mov_b32_e32 v12, s100
	v_mov_b32_e32 v13, s101
.Lwt_o_body:
	v_add_u32_e32 v14, v6, v2
	v_mul_u32_u24_e32 v14, v14, v8
	v_lshl_add_u32 v14, v7, 2, v14
	v_mov_b32_e32 v15, 0
	v_lshl_add_u64 v[14:15], v[10:11], 0, v[14:15]
	global_load_dwordx4 v[64:67], v[14:15], off
	global_load_dwordx4 v[68:71], v[14:15], off offset:16
	global_load_dwordx4 v[72:75], v[14:15], off offset:32
	global_load_dwordx4 v[76:79], v[14:15], off offset:48
	global_load_dwordx4 v[80:83], v[14:15], off offset:64
	global_load_dwordx4 v[84:87], v[14:15], off offset:80
	global_load_dwordx4 v[88:91], v[14:15], off offset:96
	global_load_dwordx4 v[92:95], v[14:15], off offset:112
	v_mul_u32_u24_e32 v16, v7, v9
	v_lshl_add_u32 v16, v6, 1, v16
	v_lshl_add_u32 v16, v2, 1, v16
	v_mov_b32_e32 v17, 0
	v_lshl_add_u64 v[16:17], v[12:13], 0, v[16:17]
	v_mov_b32_e32 v18, v9
	v_mov_b32_e32 v19, 0
	v_add_u32_e32 v0, v0, v1
	s_waitcnt vmcnt(0)
	v_cvt_pk_bf16_f32 v96, v64, v65
	v_cvt_pk_bf16_f32 v97, v66, v67
	v_cvt_pk_bf16_f32 v98, v68, v69
	v_cvt_pk_bf16_f32 v99, v70, v71
	v_cvt_pk_bf16_f32 v100, v72, v73
	v_cvt_pk_bf16_f32 v101, v74, v75
	v_cvt_pk_bf16_f32 v102, v76, v77
	v_cvt_pk_bf16_f32 v103, v78, v79
	v_cvt_pk_bf16_f32 v104, v80, v81
	v_cvt_pk_bf16_f32 v105, v82, v83
	v_cvt_pk_bf16_f32 v106, v84, v85
	v_cvt_pk_bf16_f32 v107, v86, v87
	v_cvt_pk_bf16_f32 v108, v88, v89
	v_cvt_pk_bf16_f32 v109, v90, v91
	v_cvt_pk_bf16_f32 v110, v92, v93
	v_cvt_pk_bf16_f32 v111, v94, v95
	global_store_short v[16:17], v96, off
	v_lshl_add_u64 v[16:17], v[16:17], 0, v[18:19]
	global_store_short_d16_hi v[16:17], v96, off
	v_lshl_add_u64 v[16:17], v[16:17], 0, v[18:19]
	global_store_short v[16:17], v97, off
	v_lshl_add_u64 v[16:17], v[16:17], 0, v[18:19]
	global_store_short_d16_hi v[16:17], v97, off
	v_lshl_add_u64 v[16:17], v[16:17], 0, v[18:19]
	global_store_short v[16:17], v98, off
	v_lshl_add_u64 v[16:17], v[16:17], 0, v[18:19]
	global_store_short_d16_hi v[16:17], v98, off
	v_lshl_add_u64 v[16:17], v[16:17], 0, v[18:19]
	global_store_short v[16:17], v99, off
	v_lshl_add_u64 v[16:17], v[16:17], 0, v[18:19]
	global_store_short_d16_hi v[16:17], v99, off
	v_lshl_add_u64 v[16:17], v[16:17], 0, v[18:19]
	global_store_short v[16:17], v100, off
	v_lshl_add_u64 v[16:17], v[16:17], 0, v[18:19]
	global_store_short_d16_hi v[16:17], v100, off
	v_lshl_add_u64 v[16:17], v[16:17], 0, v[18:19]
	global_store_short v[16:17], v101, off
	v_lshl_add_u64 v[16:17], v[16:17], 0, v[18:19]
	global_store_short_d16_hi v[16:17], v101, off
	v_lshl_add_u64 v[16:17], v[16:17], 0, v[18:19]
	global_store_short v[16:17], v102, off
	v_lshl_add_u64 v[16:17], v[16:17], 0, v[18:19]
	global_store_short_d16_hi v[16:17], v102, off
	v_lshl_add_u64 v[16:17], v[16:17], 0, v[18:19]
	global_store_short v[16:17], v103, off
	v_lshl_add_u64 v[16:17], v[16:17], 0, v[18:19]
	global_store_short_d16_hi v[16:17], v103, off
	v_lshl_add_u64 v[16:17], v[16:17], 0, v[18:19]
	global_store_short v[16:17], v104, off
	v_lshl_add_u64 v[16:17], v[16:17], 0, v[18:19]
	global_store_short_d16_hi v[16:17], v104, off
	v_lshl_add_u64 v[16:17], v[16:17], 0, v[18:19]
	global_store_short v[16:17], v105, off
	v_lshl_add_u64 v[16:17], v[16:17], 0, v[18:19]
	global_store_short_d16_hi v[16:17], v105, off
	v_lshl_add_u64 v[16:17], v[16:17], 0, v[18:19]
	global_store_short v[16:17], v106, off
	v_lshl_add_u64 v[16:17], v[16:17], 0, v[18:19]
	global_store_short_d16_hi v[16:17], v106, off
	v_lshl_add_u64 v[16:17], v[16:17], 0, v[18:19]
	global_store_short v[16:17], v107, off
	v_lshl_add_u64 v[16:17], v[16:17], 0, v[18:19]
	global_store_short_d16_hi v[16:17], v107, off
	v_lshl_add_u64 v[16:17], v[16:17], 0, v[18:19]
	global_store_short v[16:17], v108, off
	v_lshl_add_u64 v[16:17], v[16:17], 0, v[18:19]
	global_store_short_d16_hi v[16:17], v108, off
	v_lshl_add_u64 v[16:17], v[16:17], 0, v[18:19]
	global_store_short v[16:17], v109, off
	v_lshl_add_u64 v[16:17], v[16:17], 0, v[18:19]
	global_store_short_d16_hi v[16:17], v109, off
	v_lshl_add_u64 v[16:17], v[16:17], 0, v[18:19]
	global_store_short v[16:17], v110, off
	v_lshl_add_u64 v[16:17], v[16:17], 0, v[18:19]
	global_store_short_d16_hi v[16:17], v110, off
	v_lshl_add_u64 v[16:17], v[16:17], 0, v[18:19]
	global_store_short v[16:17], v111, off
	v_lshl_add_u64 v[16:17], v[16:17], 0, v[18:19]
	global_store_short_d16_hi v[16:17], v111, off
	s_branch .Lwt_o_loop

; #define LAS __attribute__((address_space(3)))
; __device__ __forceinline__ unsigned pk2(float lo, float hi) { return f2bf(lo) | (f2bf(hi) << 16); }
; __device__ __forceinline__ void p0_transpose_item(const float* W, int K, int N, bf16_t* WT, LAS float* scr, int item, int lane) {
;     const int nblk = N / 32, kb = item / nblk, nb = item % nblk, k0 = 64 * kb, n0 = 32 * nb;
;     float tv[32];
; #pragma unroll
;     for (int i = 0; i < 32; ++i) tv[i] = W[(size_t)(k0 + 2 * i + (lane >> 5)) * N + n0 + (lane & 31)];
; #pragma unroll
;     for (int i = 0; i < 32; ++i) scr[(2 * i + (lane >> 5)) * 33 + (lane & 31)] = tv[i];
;     asm volatile("s_waitcnt lgkmcnt(0)" ::: "memory");
;     const int c = lane & 7;
; #pragma unroll
;     for (int j = 0; j < 4; ++j) { const int n = (lane >> 3) + 8 * j; const LAS float* s = scr + (8 * c) * 33 + n;
;         u32x4 o; o.x = pk2(s[0 * 33], s[1 * 33]); o.y = pk2(s[2 * 33], s[3 * 33]); o.z = pk2(s[4 * 33], s[5 * 33]); o.w = pk2(s[6 * 33], s[7 * 33]);
;         *(u32x4*)(WT + (size_t)(n0 + n) * K + k0 + 8 * c) = o; }
;     asm volatile("s_waitcnt lgkmcnt(0)" ::: "memory");
; }
; __device__ __forceinline__ void phase0(const Params& p, LAS unsigned char* lds, int gw, int NGW, int wave, int lane) {
;     ...
;     for (int it = gw; it < NIT; it += NGW) {
;         int r = it;
;         if (r < 2 * I_EI) { const int j = r / I_EI; p0_transpose_item(p.in[8] + (size_t)j * 1024 * EIN, 1024, EIN, (bf16_t*)(ws + WS_WEI) + (size_t)j * EINP * 1024, scr, r % I_EI, lane); continue; } r -= 2 * I_EI;
;         if (r < 2 * I_EO) { const int j = r / I_EO; p0_transpose_item(p.in[9] + (size_t)j * 1024 * 1024, 1024, 1024, (bf16_t*)(ws + WS_WEO) + (size_t)j * 1024 * 1024, scr, r % I_EO, lane); continue; } r -= 2 * I_EO;
;         if (r < 2 * I_OI) { const int j = r / I_OI; p0_transpose_item(p.in[21] + (size_t)j * 1024 * OIN, 1024, OIN, (bf16_t*)(ws + WS_WOI) + (size_t)j * OIN * 1024, scr, r % I_OI, lane); continue; } r -= 2 * I_OI;
;         { const int j = r / I_OO; p0_transpose_item(p.in[22] + (size_t)j * 512 * 1024, 512, 1024, (bf16_t*)(ws + WS_WOO) + (size_t)j * 1024 * 512, scr, r % I_OO, lane); }
;     }
.Lwt_e_begin:
	v_readlane_b32 s100, v255, 18
	v_mbcnt_lo_u32_b32 v2, -1, 0
	v_mbcnt_hi_u32_b32 v2, -1, v2
	s_cmp_lg_u32 s100, 0
	s_cbranch_scc1 .Lkvc_e_done
	s_cmp_eq_u32 s90, 0x100
	s_cselect_b32 s100, 81, 0
	s_sub_u32 s101, s90, s100
	s_lshl_b32 s101, s101, 3
	v_mov_b32_e32 v1, s101
	s_sub_u32 s100, s71, s100
	s_lshl_b32 s100, s100, 3
	v_readlane_b32 s101, v251, 0
	s_nop 1
	s_add_u32 s100, s100, s101
	v_mov_b32_e32 v0, s100
	s_nop 1
.Lwt_e_loop:
	v_readfirstlane_b32 s100, v0
	s_nop 1
	s_cmp_ge_u32 s100, 5952
	s_cbranch_scc1 .Lkvc_e_done
	s_cmp_lt_u32 s100, 2112
	s_cbranch_scc1 .Lwt_e_c0
	s_cmp_lt_u32 s100, 2624
	s_cbranch_scc1 .Lwt_e_c1
	s_cmp_lt_u32 s100, 3136
	s_cbranch_scc1 .Lwt_e_c2
	s_cmp_lt_u32 s100, 5696
	s_cbranch_scc1 .Lwt_e_c3
	s_branch .Lwt_e_c4
.Lwt_e_c0:
	v_mov_b32_e32 v20, v0
	v_mov_b32_e32 v4, 0x1f07c20
	v_mul_hi_u32 v6, v20, v4
	v_mul_u32_u24_e32 v7, 132, v6
	v_sub_u32_e32 v7, v20, v7
	v_lshlrev_b32_e32 v6, 6, v6
	v_lshlrev_b32_e32 v7, 5, v7
	v_mov_b32_e32 v8, 0x4200
	v_mov_b32_e32 v9, 0x800
	v_readlane_b32 s100, v251, 25
	v_readlane_b32 s101, v251, 26
	s_nop 1
	s_add_u32 s100, s100, 0x1080000
	s_addc_u32 s101, s101, 0
	v_mov_b32_e32 v10, s100
	v_mov_b32_e32 v11, s101
	s_add_u32 s100, s88, 0x880000
	s_addc_u32 s101, s89, 0
	v_mov_b32_e32 v12, s100
	v_mov_b32_e32 v13, s101
	s_branch .Lwt_e_body
.Lwt_e_c1:
	v_subrev_u32_e32 v20, 2112, v0
	v_mov_b32_e32 v4, 0x8000000
	v_mul_hi_u32 v6, v20, v4
	v_mul_u32_u24_e32 v7, 32, v6
	v_sub_u32_e32 v7, v20, v7
	v_lshlrev_b32_e32 v6, 6, v6
	v_lshlrev_b32_e32 v7, 5, v7
	v_mov_b32_e32 v8, 0x1000
	v_mov_b32_e32 v9, 0x800
	v_readlane_b32 s100, v251, 27
	v_readlane_b32 s101, v251, 28
	s_nop 1
	v_mov_b32_e32 v10, s100
	v_mov_b32_e32 v11, s101
	s_add_u32 s100, s88, 0x1100000
	s_addc_u32 s101, s89, 0
	v_mov_b32_e32 v12, s100
	v_mov_b32_e32 v13, s101
	s_branch .Lwt_e_body
.Lwt_e_c2:
	v_subrev_u32_e32 v20, 2624, v0
	v_mov_b32_e32 v4, 0x8000000
	v_mul_hi_u32 v6, v20, v4
	v_mul_u32_u24_e32 v7, 32, v6
	v_sub_u32_e32 v7, v20, v7
	v_lshlrev_b32_e32 v6, 6, v6
	v_lshlrev_b32_e32 v7, 5, v7
	v_mov_b32_e32 v8, 0x1000
	v_mov_b32_e32 v9, 0x800
	v_readlane_b32 s100, v251, 27
	v_readlane_b32 s101, v251, 28
	s_nop 1
	s_add_u32 s100, s100, 0x400000
	s_addc_u32 s101, s101, 0
	v_mov_b32_e32 v10, s100
	v_mov_b32_e32 v11, s101
	s_add_u32 s100, s88, 0x1300000
	s_addc_u32 s101, s89, 0
	v_mov_b32_e32 v12, s100
	v_mov_b32_e32 v13, s101
	s_branch .Lwt_e_body
.Lwt_e_c3:
	v_subrev_u32_e32 v20, 3136, v0
	v_mov_b32_e32 v4, 0x199999a
	v_mul_hi_u32 v6, v20, v4
	v_mul_u32_u24_e32 v7, 160, v6
	v_sub_u32_e32 v7, v20, v7
	v_lshlrev_b32_e32 v6, 6, v6
	v_lshlrev_b32_e32 v7, 5, v7
	v_mov_b32_e32 v8, 0x5000
	v_mov_b32_e32 v9, 0x800
	v_readlane_b32 s100, v251, 51
	v_readlane_b32 s101, v251, 52
	s_nop 1
	v_mov_b32_e32 v10, s100
	v_mov_b32_e32 v11, s101
	s_add_u32 s100, s88, 0x1500000
	s_addc_u32 s101, s89, 0
	v_mov_b32_e32 v12, s100
	v_mov_b32_e32 v13, s101
	s_branch .Lwt_e_body
.Lwt_e_c4:
	v_subrev_u32_e32 v20, 5696, v0
	v_mov_b32_e32 v4, 0x8000000
	v_mul_hi_u32 v6, v20, v4
	v_mul_u32_u24_e32 v7, 32, v6
	v_sub_u32_e32 v7, v20, v7
	v_lshlrev_b32_e32 v6, 6, v6
	v_lshlrev_b32_e32 v7, 5, v7
	v_mov_b32_e32 v8, 0x1000
	v_mov_b32_e32 v9, 0x400
	v_readlane_b32 s100, v251, 53
	v_readlane_b32 s101, v251, 54
	s_nop 1
	v_mov_b32_e32 v10, s100
	v_mov_b32_e32 v11, s101
	s_add_u32 s100, s88, 0x2900000
	s_addc_u32 s101, s89, 0
	v_mov_b32_e32 v12, s100
	v_mov_b32_e32 v13, s101
